# MIXB/MB 8x64 blocked layout + the v111 policies (P9 stores default)
# speedup vs baseline: 1.0066x; 1.0066x over previous
.LBB0_957:
	v_mul_f32_e32 v157, v125, v125
	v_mul_f32_e32 v160, v127, v127
	v_fmac_f32_e32 v157, v124, v124
	v_fmac_f32_e32 v160, v126, v126
	v_add_f32_e32 v157, v157, v160
	v_mul_f32_e32 v160, v121, v121
	v_fmac_f32_e32 v160, v120, v120
	v_cvt_pk_bf16_f32 v124, v124, v125
	v_cvt_pk_bf16_f32 v125, v126, v127
	v_cvt_pk_bf16_f32 v126, v120, v121
	v_mul_f32_e32 v120, v117, v117
	v_mul_f32_e32 v121, v119, v119
	v_fmac_f32_e32 v120, v116, v116
	v_fmac_f32_e32 v121, v118, v118
	v_add_f32_e32 v120, v120, v121
	v_mul_f32_e32 v121, v113, v113
	v_and_b32_e32 v155, 64, v154
	v_fmac_f32_e32 v121, v112, v112
	v_xor_b32_e32 v147, 16, v154
	v_add_u32_e32 v155, 64, v155
	v_add_f32_e32 v157, v157, v160
	v_mul_f32_e32 v160, v123, v123
	v_add_f32_e32 v120, v120, v121
	v_mul_f32_e32 v121, v115, v115
	v_cmp_lt_i32_e32 vcc, v147, v155
	v_fmac_f32_e32 v160, v122, v122
	v_fmac_f32_e32 v121, v114, v114
	v_cndmask_b32_e32 v147, v154, v147, vcc
	v_add_f32_e32 v157, v160, v157
	v_add_f32_e32 v120, v121, v120
	v_lshlrev_b32_e32 v156, 2, v147
	v_xor_b32_e32 v147, 32, v154
	v_cvt_pk_bf16_f32 v127, v122, v123
	v_add_f32_e32 v122, v157, v120
	v_cmp_lt_i32_e32 vcc, v147, v155
	ds_bpermute_b32 v123, v156, v122
	v_lshl_add_u32 v146, s30, 8, v148
	v_cndmask_b32_e32 v147, v154, v147, vcc
	v_lshlrev_b32_e32 v155, 2, v147
	v_ashrrev_i32_e32 v147, 31, v146
	v_and_b32_e32 v214, 0x40, v150
	v_and_b32_e32 v215, 0x38, v150
	v_lshlrev_b32_e32 v214, 7, v214
	v_lshl_or_b32 v214, v215, 1, v214
	v_and_b32_e32 v215, 7, v148
	v_mul_u32_u24_e32 v215, 0x780, v215
	v_sub_u32_e32 v214, v214, v215
	v_lshl_add_u32 v144, s14, 11, v214
	v_lshlrev_b64 v[158:159], 11, v[146:147]
	v_ashrrev_i32_e32 v145, 31, v144
	v_lshl_add_u64 v[120:121], s[66:67], 0, v[158:159]
	v_lshl_add_u64 v[158:159], v[144:145], 0, v[120:121]
	v_cvt_pk_bf16_f32 v120, v116, v117
	s_waitcnt lgkmcnt(0)
	v_add_f32_e32 v116, v122, v123
	ds_bpermute_b32 v117, v155, v116
	s_lshl_b32 s30, s14, 2
	s_ashr_i32 s31, s30, 31
	v_cvt_pk_bf16_f32 v121, v118, v119
	v_cvt_pk_bf16_f32 v122, v112, v113
	v_cvt_pk_bf16_f32 v123, v114, v115
	global_store_dwordx4 v[158:159], v[124:127], off
	global_store_dwordx4 v[158:159], v[120:123], off offset:1024
	s_and_saveexec_b64 s[34:35], s[4:5]
	s_cbranch_execz .LBB0_959
	v_lshlrev_b64 v[112:113], 6, v[146:147]
	v_lshl_add_u64 v[112:113], s[0:1], 0, v[112:113]
	v_lshl_add_u64 v[112:113], s[30:31], 2, v[112:113]
	s_lshl_b32 s14, s45, 2
	s_waitcnt lgkmcnt(0)
	v_add_f32_e32 v114, v116, v117
	v_lshl_add_u64 v[112:113], v[112:113], 0, s[14:15]
	global_store_dword v[112:113], v114, off
.LBB0_959:
	s_or_b64 exec, exec, s[34:35]
	v_mul_f32_e32 v116, v109, v109
	s_waitcnt lgkmcnt(0)
	v_mul_f32_e32 v117, v111, v111
	v_fmac_f32_e32 v116, v108, v108
	v_fmac_f32_e32 v117, v110, v110
	v_add_f32_e32 v116, v116, v117
	v_mul_f32_e32 v117, v105, v105
	v_fmac_f32_e32 v117, v104, v104
	v_cvt_pk_bf16_f32 v108, v108, v109
	v_cvt_pk_bf16_f32 v109, v110, v111
	v_cvt_pk_bf16_f32 v110, v104, v105
	v_mul_f32_e32 v104, v101, v101
	v_mul_f32_e32 v105, v103, v103
	v_fmac_f32_e32 v104, v100, v100
	v_fmac_f32_e32 v105, v102, v102
	v_add_f32_e32 v104, v104, v105
	v_mul_f32_e32 v105, v97, v97
	v_fmac_f32_e32 v105, v96, v96
	v_add_f32_e32 v116, v116, v117
	v_mul_f32_e32 v117, v107, v107
	v_add_f32_e32 v104, v104, v105
	v_mul_f32_e32 v105, v99, v99
	v_fmac_f32_e32 v117, v106, v106
	v_fmac_f32_e32 v105, v98, v98
	v_add_f32_e32 v116, v117, v116
	v_add_f32_e32 v104, v105, v104
	v_cvt_pk_bf16_f32 v111, v106, v107
	v_add_f32_e32 v106, v116, v104
	ds_bpermute_b32 v107, v156, v106
	v_or_b32_e32 v112, 16, v146
	v_ashrrev_i32_e32 v113, 31, v112
	v_lshlrev_b64 v[114:115], 11, v[112:113]
	v_lshl_add_u64 v[104:105], s[66:67], 0, v[114:115]
	v_lshl_add_u64 v[114:115], v[144:145], 0, v[104:105]
	v_cvt_pk_bf16_f32 v104, v100, v101
	s_waitcnt lgkmcnt(0)
	v_add_f32_e32 v100, v106, v107
	ds_bpermute_b32 v101, v155, v100
	v_cvt_pk_bf16_f32 v105, v102, v103
	v_cvt_pk_bf16_f32 v106, v96, v97
	v_cvt_pk_bf16_f32 v107, v98, v99
	global_store_dwordx4 v[114:115], v[108:111], off
	global_store_dwordx4 v[114:115], v[104:107], off offset:1024
	s_and_saveexec_b64 s[34:35], s[4:5]
	s_cbranch_execz .LBB0_961
	v_lshlrev_b64 v[96:97], 6, v[112:113]
	v_lshl_add_u64 v[96:97], s[0:1], 0, v[96:97]
	v_lshl_add_u64 v[96:97], s[30:31], 2, v[96:97]
	s_lshl_b32 s14, s45, 2
	s_waitcnt lgkmcnt(0)
	v_add_f32_e32 v98, v100, v101
	v_lshl_add_u64 v[96:97], v[96:97], 0, s[14:15]
	global_store_dword v[96:97], v98, off
.LBB0_961:
	s_or_b64 exec, exec, s[34:35]
	v_mul_f32_e32 v100, v93, v93
	s_waitcnt lgkmcnt(0)
	v_mul_f32_e32 v101, v95, v95
	v_fmac_f32_e32 v100, v92, v92
	v_fmac_f32_e32 v101, v94, v94
	v_add_f32_e32 v100, v100, v101
	v_mul_f32_e32 v101, v89, v89
	v_fmac_f32_e32 v101, v88, v88
	v_cvt_pk_bf16_f32 v92, v92, v93
	v_cvt_pk_bf16_f32 v93, v94, v95
	v_cvt_pk_bf16_f32 v94, v88, v89
	v_mul_f32_e32 v88, v85, v85
	v_mul_f32_e32 v89, v87, v87
	v_fmac_f32_e32 v88, v84, v84
	v_fmac_f32_e32 v89, v86, v86
	v_add_f32_e32 v88, v88, v89
	v_mul_f32_e32 v89, v81, v81
	v_fmac_f32_e32 v89, v80, v80
	v_add_f32_e32 v100, v100, v101
	v_mul_f32_e32 v101, v91, v91
	v_add_f32_e32 v88, v88, v89
	v_mul_f32_e32 v89, v83, v83
	v_fmac_f32_e32 v101, v90, v90
	v_fmac_f32_e32 v89, v82, v82
	v_add_f32_e32 v100, v101, v100
	v_add_f32_e32 v88, v89, v88
	v_cvt_pk_bf16_f32 v95, v90, v91
	v_add_f32_e32 v90, v100, v88
	ds_bpermute_b32 v91, v156, v90
	v_or_b32_e32 v96, 32, v146
	v_ashrrev_i32_e32 v97, 31, v96
	v_lshlrev_b64 v[98:99], 11, v[96:97]
	v_lshl_add_u64 v[88:89], s[66:67], 0, v[98:99]
	v_lshl_add_u64 v[98:99], v[144:145], 0, v[88:89]
	v_cvt_pk_bf16_f32 v88, v84, v85
	s_waitcnt lgkmcnt(0)
	v_add_f32_e32 v84, v90, v91
	ds_bpermute_b32 v85, v155, v84
	v_cvt_pk_bf16_f32 v89, v86, v87
	v_cvt_pk_bf16_f32 v90, v80, v81
	v_cvt_pk_bf16_f32 v91, v82, v83
	global_store_dwordx4 v[98:99], v[92:95], off
	global_store_dwordx4 v[98:99], v[88:91], off offset:1024
	s_and_saveexec_b64 s[34:35], s[4:5]
	s_cbranch_execz .LBB0_963
	v_lshlrev_b64 v[80:81], 6, v[96:97]
	v_lshl_add_u64 v[80:81], s[0:1], 0, v[80:81]
	v_lshl_add_u64 v[80:81], s[30:31], 2, v[80:81]
	s_lshl_b32 s14, s45, 2
	s_waitcnt lgkmcnt(0)
	v_add_f32_e32 v82, v84, v85
	v_lshl_add_u64 v[80:81], v[80:81], 0, s[14:15]
	global_store_dword v[80:81], v82, off
.LBB0_963:
	s_or_b64 exec, exec, s[34:35]
	v_mul_f32_e32 v84, v77, v77
	s_waitcnt lgkmcnt(0)
	v_mul_f32_e32 v85, v79, v79
	v_fmac_f32_e32 v84, v76, v76
	v_fmac_f32_e32 v85, v78, v78
	v_add_f32_e32 v84, v84, v85
	v_mul_f32_e32 v85, v73, v73
	v_fmac_f32_e32 v85, v72, v72
	v_cvt_pk_bf16_f32 v76, v76, v77
	v_cvt_pk_bf16_f32 v77, v78, v79
	v_cvt_pk_bf16_f32 v78, v72, v73
	v_mul_f32_e32 v72, v69, v69
	v_mul_f32_e32 v73, v71, v71
	v_fmac_f32_e32 v72, v68, v68
	v_fmac_f32_e32 v73, v70, v70
	v_add_f32_e32 v72, v72, v73
	v_mul_f32_e32 v73, v65, v65
	v_fmac_f32_e32 v73, v64, v64
	v_add_f32_e32 v84, v84, v85
	v_mul_f32_e32 v85, v75, v75
	v_add_f32_e32 v72, v72, v73
	v_mul_f32_e32 v73, v67, v67
	v_fmac_f32_e32 v85, v74, v74
	v_fmac_f32_e32 v73, v66, v66
	v_add_f32_e32 v84, v85, v84
	v_add_f32_e32 v72, v73, v72
	v_cvt_pk_bf16_f32 v79, v74, v75
	v_add_f32_e32 v74, v84, v72
	ds_bpermute_b32 v75, v156, v74
	v_or_b32_e32 v80, 48, v146
	v_ashrrev_i32_e32 v81, 31, v80
	v_lshlrev_b64 v[82:83], 11, v[80:81]
	v_lshl_add_u64 v[72:73], s[66:67], 0, v[82:83]
	v_lshl_add_u64 v[82:83], v[144:145], 0, v[72:73]
	v_cvt_pk_bf16_f32 v72, v68, v69
	s_waitcnt lgkmcnt(0)
	v_add_f32_e32 v68, v74, v75
	ds_bpermute_b32 v69, v155, v68
	v_cvt_pk_bf16_f32 v73, v70, v71
	v_cvt_pk_bf16_f32 v74, v64, v65
	v_cvt_pk_bf16_f32 v75, v66, v67
	global_store_dwordx4 v[82:83], v[76:79], off
	global_store_dwordx4 v[82:83], v[72:75], off offset:1024
	s_and_saveexec_b64 s[34:35], s[4:5]
	s_cbranch_execz .LBB0_965
	v_lshlrev_b64 v[64:65], 6, v[80:81]
	v_lshl_add_u64 v[64:65], s[0:1], 0, v[64:65]
	v_lshl_add_u64 v[64:65], s[30:31], 2, v[64:65]
	s_lshl_b32 s14, s45, 2
	s_waitcnt lgkmcnt(0)
	v_add_f32_e32 v66, v68, v69
	v_lshl_add_u64 v[64:65], v[64:65], 0, s[14:15]
	global_store_dword v[64:65], v66, off
.LBB0_965:
	s_or_b64 exec, exec, s[34:35]
	v_mul_f32_e32 v68, v61, v61
	s_waitcnt lgkmcnt(0)
	v_mul_f32_e32 v69, v63, v63
	v_fmac_f32_e32 v68, v60, v60
	v_fmac_f32_e32 v69, v62, v62
	v_add_f32_e32 v68, v68, v69
	v_mul_f32_e32 v69, v57, v57
	v_fmac_f32_e32 v69, v56, v56
	v_cvt_pk_bf16_f32 v60, v60, v61
	v_cvt_pk_bf16_f32 v61, v62, v63
	v_cvt_pk_bf16_f32 v62, v56, v57
	v_mul_f32_e32 v56, v53, v53
	v_mul_f32_e32 v57, v55, v55
	v_fmac_f32_e32 v56, v52, v52
	v_fmac_f32_e32 v57, v54, v54
	v_add_f32_e32 v56, v56, v57
	v_mul_f32_e32 v57, v49, v49
	v_fmac_f32_e32 v57, v48, v48
	v_add_f32_e32 v68, v68, v69
	v_mul_f32_e32 v69, v59, v59
	v_add_f32_e32 v56, v56, v57
	v_mul_f32_e32 v57, v51, v51
	v_fmac_f32_e32 v69, v58, v58
	v_fmac_f32_e32 v57, v50, v50
	v_add_f32_e32 v68, v69, v68
	v_add_f32_e32 v56, v57, v56
	v_cvt_pk_bf16_f32 v63, v58, v59
	v_add_f32_e32 v58, v68, v56
	ds_bpermute_b32 v59, v156, v58
	v_add_u32_e32 v64, 0x80, v146
	v_ashrrev_i32_e32 v65, 31, v64
	v_lshlrev_b64 v[66:67], 11, v[64:65]
	v_lshl_add_u64 v[56:57], s[66:67], 0, v[66:67]
	v_lshl_add_u64 v[66:67], v[144:145], 0, v[56:57]
	v_cvt_pk_bf16_f32 v56, v52, v53
	s_waitcnt lgkmcnt(0)
	v_add_f32_e32 v52, v58, v59
	ds_bpermute_b32 v53, v155, v52
	v_cvt_pk_bf16_f32 v57, v54, v55
	v_cvt_pk_bf16_f32 v58, v48, v49
	v_cvt_pk_bf16_f32 v59, v50, v51
	global_store_dwordx4 v[66:67], v[60:63], off
	global_store_dwordx4 v[66:67], v[56:59], off offset:1024
	s_and_saveexec_b64 s[34:35], s[4:5]
	s_cbranch_execz .LBB0_967
	v_lshlrev_b64 v[48:49], 6, v[64:65]
	v_lshl_add_u64 v[48:49], s[0:1], 0, v[48:49]
	v_lshl_add_u64 v[48:49], s[30:31], 2, v[48:49]
	s_lshl_b32 s14, s45, 2
	s_waitcnt lgkmcnt(0)
	v_add_f32_e32 v50, v52, v53
	v_lshl_add_u64 v[48:49], v[48:49], 0, s[14:15]
	global_store_dword v[48:49], v50, off
.LBB0_967:
	s_or_b64 exec, exec, s[34:35]
	v_mul_f32_e32 v52, v45, v45
	s_waitcnt lgkmcnt(0)
	v_mul_f32_e32 v53, v47, v47
	v_fmac_f32_e32 v52, v44, v44
	v_fmac_f32_e32 v53, v46, v46
	v_add_f32_e32 v52, v52, v53
	v_mul_f32_e32 v53, v41, v41
	v_fmac_f32_e32 v53, v40, v40
	v_cvt_pk_bf16_f32 v44, v44, v45
	v_cvt_pk_bf16_f32 v45, v46, v47
	v_cvt_pk_bf16_f32 v46, v40, v41
	v_mul_f32_e32 v40, v37, v37
	v_mul_f32_e32 v41, v39, v39
	v_fmac_f32_e32 v40, v36, v36
	v_fmac_f32_e32 v41, v38, v38
	v_add_f32_e32 v40, v40, v41
	v_mul_f32_e32 v41, v33, v33
	v_fmac_f32_e32 v41, v32, v32
	v_add_f32_e32 v52, v52, v53
	v_mul_f32_e32 v53, v43, v43
	v_add_f32_e32 v40, v40, v41
	v_mul_f32_e32 v41, v35, v35
	v_fmac_f32_e32 v53, v42, v42
	v_fmac_f32_e32 v41, v34, v34
	v_add_f32_e32 v52, v53, v52
	v_add_f32_e32 v40, v41, v40
	v_cvt_pk_bf16_f32 v47, v42, v43
	v_add_f32_e32 v42, v52, v40
	ds_bpermute_b32 v43, v156, v42
	v_add_u32_e32 v48, 0x90, v146
	v_ashrrev_i32_e32 v49, 31, v48
	v_lshlrev_b64 v[50:51], 11, v[48:49]
	v_lshl_add_u64 v[40:41], s[66:67], 0, v[50:51]
	v_lshl_add_u64 v[50:51], v[144:145], 0, v[40:41]
	v_cvt_pk_bf16_f32 v40, v36, v37
	s_waitcnt lgkmcnt(0)
	v_add_f32_e32 v36, v42, v43
	ds_bpermute_b32 v37, v155, v36
	v_cvt_pk_bf16_f32 v41, v38, v39
	v_cvt_pk_bf16_f32 v42, v32, v33
	v_cvt_pk_bf16_f32 v43, v34, v35
	global_store_dwordx4 v[50:51], v[44:47], off
	global_store_dwordx4 v[50:51], v[40:43], off offset:1024
	s_and_saveexec_b64 s[34:35], s[4:5]
	s_cbranch_execz .LBB0_969
	v_lshlrev_b64 v[32:33], 6, v[48:49]
	v_lshl_add_u64 v[32:33], s[0:1], 0, v[32:33]
	v_lshl_add_u64 v[32:33], s[30:31], 2, v[32:33]
	s_lshl_b32 s14, s45, 2
	s_waitcnt lgkmcnt(0)
	v_add_f32_e32 v34, v36, v37
	v_lshl_add_u64 v[32:33], v[32:33], 0, s[14:15]
	global_store_dword v[32:33], v34, off
.LBB0_969:
	s_or_b64 exec, exec, s[34:35]
	v_mul_f32_e32 v36, v29, v29
	s_waitcnt lgkmcnt(0)
	v_mul_f32_e32 v37, v31, v31
	v_fmac_f32_e32 v36, v28, v28
	v_fmac_f32_e32 v37, v30, v30
	v_add_f32_e32 v36, v36, v37
	v_mul_f32_e32 v37, v25, v25
	v_fmac_f32_e32 v37, v24, v24
	v_cvt_pk_bf16_f32 v28, v28, v29
	v_cvt_pk_bf16_f32 v29, v30, v31
	v_cvt_pk_bf16_f32 v30, v24, v25
	v_mul_f32_e32 v24, v21, v21
	v_mul_f32_e32 v25, v23, v23
	v_fmac_f32_e32 v24, v20, v20
	v_fmac_f32_e32 v25, v22, v22
	v_add_f32_e32 v24, v24, v25
	v_mul_f32_e32 v25, v17, v17
	v_fmac_f32_e32 v25, v16, v16
	v_add_f32_e32 v36, v36, v37
	v_mul_f32_e32 v37, v27, v27
	v_add_f32_e32 v24, v24, v25
	v_mul_f32_e32 v25, v19, v19
	v_fmac_f32_e32 v37, v26, v26
	v_fmac_f32_e32 v25, v18, v18
	v_add_f32_e32 v36, v37, v36
	v_add_f32_e32 v24, v25, v24
	v_cvt_pk_bf16_f32 v31, v26, v27
	v_add_f32_e32 v26, v36, v24
	ds_bpermute_b32 v27, v156, v26
	v_add_u32_e32 v32, 0xa0, v146
	v_ashrrev_i32_e32 v33, 31, v32
	v_lshlrev_b64 v[34:35], 11, v[32:33]
	v_lshl_add_u64 v[24:25], s[66:67], 0, v[34:35]
	v_lshl_add_u64 v[34:35], v[144:145], 0, v[24:25]
	v_cvt_pk_bf16_f32 v24, v20, v21
	s_waitcnt lgkmcnt(0)
	v_add_f32_e32 v20, v26, v27
	ds_bpermute_b32 v21, v155, v20
	v_cvt_pk_bf16_f32 v25, v22, v23
	v_cvt_pk_bf16_f32 v26, v16, v17
	v_cvt_pk_bf16_f32 v27, v18, v19
	global_store_dwordx4 v[34:35], v[28:31], off
	global_store_dwordx4 v[34:35], v[24:27], off offset:1024
	s_and_saveexec_b64 s[34:35], s[4:5]
	s_cbranch_execz .LBB0_971
	v_lshlrev_b64 v[16:17], 6, v[32:33]
	v_lshl_add_u64 v[16:17], s[0:1], 0, v[16:17]
	v_lshl_add_u64 v[16:17], s[30:31], 2, v[16:17]
	s_lshl_b32 s14, s45, 2
	s_waitcnt lgkmcnt(0)
	v_add_f32_e32 v18, v20, v21
	v_lshl_add_u64 v[16:17], v[16:17], 0, s[14:15]
	global_store_dword v[16:17], v18, off
.LBB0_971:
	s_or_b64 exec, exec, s[34:35]
	v_mul_f32_e32 v20, v13, v13
	s_waitcnt lgkmcnt(0)
	v_mul_f32_e32 v21, v15, v15
	v_fmac_f32_e32 v20, v12, v12
	v_fmac_f32_e32 v21, v14, v14
	v_add_f32_e32 v20, v20, v21
	v_mul_f32_e32 v21, v9, v9
	v_fmac_f32_e32 v21, v8, v8
	v_cvt_pk_bf16_f32 v12, v12, v13
	v_cvt_pk_bf16_f32 v13, v14, v15
	v_cvt_pk_bf16_f32 v14, v8, v9
	v_mul_f32_e32 v8, v5, v5
	v_mul_f32_e32 v9, v7, v7
	v_fmac_f32_e32 v8, v4, v4
	v_fmac_f32_e32 v9, v6, v6
	v_add_f32_e32 v8, v8, v9
	v_mul_f32_e32 v9, v1, v1
	v_fmac_f32_e32 v9, v0, v0
	v_add_f32_e32 v20, v20, v21
	v_mul_f32_e32 v21, v11, v11
	v_add_f32_e32 v8, v8, v9
	v_mul_f32_e32 v9, v3, v3
	v_fmac_f32_e32 v21, v10, v10
	v_fmac_f32_e32 v9, v2, v2
	v_add_f32_e32 v20, v21, v20
	v_add_f32_e32 v8, v9, v8
	v_cvt_pk_bf16_f32 v15, v10, v11
	v_add_f32_e32 v10, v20, v8
	ds_bpermute_b32 v11, v156, v10
	v_add_u32_e32 v16, 0xb0, v146
	v_ashrrev_i32_e32 v17, 31, v16
	v_lshlrev_b64 v[18:19], 11, v[16:17]
	v_lshl_add_u64 v[8:9], s[66:67], 0, v[18:19]
	v_lshl_add_u64 v[18:19], v[144:145], 0, v[8:9]
	v_cvt_pk_bf16_f32 v8, v4, v5
	s_waitcnt lgkmcnt(0)
	v_add_f32_e32 v4, v10, v11
	ds_bpermute_b32 v5, v155, v4
	v_cvt_pk_bf16_f32 v9, v6, v7
	v_cvt_pk_bf16_f32 v10, v0, v1
	v_cvt_pk_bf16_f32 v11, v2, v3
	global_store_dwordx4 v[18:19], v[12:15], off
	global_store_dwordx4 v[18:19], v[8:11], off offset:1024
	s_and_saveexec_b64 s[34:35], s[4:5]
	s_cbranch_execz .LBB0_973
	v_lshlrev_b64 v[0:1], 6, v[16:17]
	v_lshl_add_u64 v[0:1], s[0:1], 0, v[0:1]
	v_lshl_add_u64 v[0:1], s[30:31], 2, v[0:1]
	s_lshl_b32 s14, s45, 2
	s_waitcnt lgkmcnt(0)
	v_add_f32_e32 v2, v4, v5
	v_lshl_add_u64 v[0:1], v[0:1], 0, s[14:15]
	global_store_dword v[0:1], v2, off
